# prologue weight transpose: plain tiles issue their 8 element loads + scale loads together (was one serialized round trip per element); sg_unit bias loads hoisted; GLA-prep operand packing deferred to
# speedup vs baseline: 1.0496x; 1.0266x over previous
.LBB0_465:
	s_lshl_b32 s26, s18, 2
	v_add_u32_e32 v9, s20, v2
	v_mul_lo_u32 v8, v9, s26
	v_add_u32_e32 v8, v8, v4
	global_load_dword v22, v8, s[4:5]
	v_add_u32_e32 v8, s26, v8
	global_load_dword v23, v8, s[4:5]
	v_add_u32_e32 v8, s26, v8
	global_load_dword v24, v8, s[4:5]
	v_add_u32_e32 v8, s26, v8
	global_load_dword v25, v8, s[4:5]
	v_add_u32_e32 v8, s26, v8
	global_load_dword v26, v8, s[4:5]
	v_add_u32_e32 v8, s26, v8
	global_load_dword v27, v8, s[4:5]
	v_add_u32_e32 v8, s26, v8
	global_load_dword v28, v8, s[4:5]
	v_add_u32_e32 v8, s26, v8
	global_load_dword v7, v8, s[4:5]
	s_cmp_eq_u64 s[16:17], 0
	s_cbranch_scc1 .Lpro_ns0
	v_lshlrev_b32_e32 v9, 2, v9
	global_load_dwordx4 v[30:33], v9, s[16:17]
	global_load_dwordx4 v[34:37], v9, s[16:17] offset:16
	s_waitcnt vmcnt(0)
	v_mul_f32_e32 v22, v22, v30
	v_mul_f32_e32 v23, v23, v31
	v_mul_f32_e32 v24, v24, v32
	v_mul_f32_e32 v25, v25, v33
	v_mul_f32_e32 v26, v26, v34
	v_mul_f32_e32 v27, v27, v35
	v_mul_f32_e32 v28, v28, v36
	v_mul_f32_e32 v7, v7, v37
.Lpro_ns0:
	s_waitcnt vmcnt(0)
	ds_write_b32 v19, v22
	ds_write_b32 v19, v23 offset:260
	ds_write_b32 v19, v24 offset:520
	ds_write_b32 v19, v25 offset:780
	ds_write_b32 v19, v26 offset:1040
	ds_write_b32 v19, v27 offset:1300
	ds_write_b32 v19, v28 offset:1560
	s_branch .LBB0_110

.LBB0_473:
	s_lshl_b32 s28, s20, 2
	v_add_u32_e32 v9, s22, v2
	v_mul_lo_u32 v8, v9, s28
	v_add_u32_e32 v8, v8, v4
	global_load_dword v22, v8, s[6:7]
	v_add_u32_e32 v8, s28, v8
	global_load_dword v23, v8, s[6:7]
	v_add_u32_e32 v8, s28, v8
	global_load_dword v24, v8, s[6:7]
	v_add_u32_e32 v8, s28, v8
	global_load_dword v25, v8, s[6:7]
	v_add_u32_e32 v8, s28, v8
	global_load_dword v26, v8, s[6:7]
	v_add_u32_e32 v8, s28, v8
	global_load_dword v27, v8, s[6:7]
	v_add_u32_e32 v8, s28, v8
	global_load_dword v28, v8, s[6:7]
	v_add_u32_e32 v8, s28, v8
	global_load_dword v7, v8, s[6:7]
	s_cmp_eq_u64 s[18:19], 0
	s_cbranch_scc1 .Lpro_ns1
	v_lshlrev_b32_e32 v9, 2, v9
	global_load_dwordx4 v[30:33], v9, s[18:19]
	global_load_dwordx4 v[34:37], v9, s[18:19] offset:16
	s_waitcnt vmcnt(0)
	v_mul_f32_e32 v22, v22, v30
	v_mul_f32_e32 v23, v23, v31
	v_mul_f32_e32 v24, v24, v32
	v_mul_f32_e32 v25, v25, v33
	v_mul_f32_e32 v26, v26, v34
	v_mul_f32_e32 v27, v27, v35
	v_mul_f32_e32 v28, v28, v36
	v_mul_f32_e32 v7, v7, v37
.Lpro_ns1:
	s_waitcnt vmcnt(0)
	ds_write_b32 v19, v22 offset:16896
	ds_write_b32 v19, v23 offset:17156
	ds_write_b32 v19, v24 offset:17416
	ds_write_b32 v19, v25 offset:17676
	ds_write_b32 v19, v26 offset:17936
	ds_write_b32 v19, v27 offset:18196
	ds_write_b32 v19, v28 offset:18456
	s_branch .LBB0_211

.Lpro_ns2:
	s_waitcnt vmcnt(0)
	ds_write_b32 v19, v22 offset:33792
	ds_write_b32 v19, v23 offset:34052
	ds_write_b32 v19, v24 offset:34312
	ds_write_b32 v19, v25 offset:34572
	ds_write_b32 v19, v26 offset:34832
	ds_write_b32 v19, v27 offset:35092
	ds_write_b32 v19, v28 offset:35352
	s_branch .LBB0_312

.Lpro_ns3:
	s_waitcnt vmcnt(0)
	ds_write_b32 v19, v22 offset:50688
	ds_write_b32 v19, v23 offset:50948
	ds_write_b32 v19, v24 offset:51208
	ds_write_b32 v19, v25 offset:51468
	ds_write_b32 v19, v26 offset:51728
	ds_write_b32 v19, v27 offset:51988
	ds_write_b32 v19, v28 offset:52248
	s_branch .LBB0_413

.LBB0_732:
	s_lshl_b32 s1, s12, 7
	s_and_b32 s4, s1, 0xffffc000
	s_ashr_i32 s5, s4, 31
	v_and_b32_e32 v99, 15, v1
	s_and_b32 s0, s12, 0xffffffc0
	s_lshl_b64 s[4:5], s[4:5], 2
	v_lshrrev_b32_e32 v98, 4, v0
	s_add_u32 s4, s25, s4
	v_readlane_b32 s1, v255, 23
	v_lshlrev_b32_e32 v0, 9, v99
	s_addc_u32 s5, s1, s5
	v_lshl_or_b32 v16, v98, 5, v0
	v_lshl_add_u64 v[102:103], s[4:5], 0, v[16:17]
	v_add_co_u32_e32 v50, vcc, s77, v102
	s_movk_i32 s1, 0x4000
	s_nop 0
	v_addc_co_u32_e32 v51, vcc, 0, v103, vcc
	s_mov_b64 s[10:11], 0x2000
	v_add_co_u32_e32 v46, vcc, s1, v102
	v_lshl_add_u64 v[14:15], v[102:103], 0, s[10:11]
	s_nop 0
	v_addc_co_u32_e32 v47, vcc, 0, v103, vcc
	s_movk_i32 s10, 0x6000
	s_waitcnt lgkmcnt(0)
	s_barrier
	s_mov_b64 s[16:17], 0x4000
	v_add_co_u32_e32 v48, vcc, s10, v102
	global_load_dwordx4 v[2:5], v16, s[4:5] offset:16
	global_load_dwordx4 v[6:9], v16, s[4:5]
	global_load_dwordx4 v[10:13], v[50:51], off
	global_load_dwordx4 v[18:21], v[14:15], off offset:16
	v_lshl_add_u64 v[14:15], v[102:103], 0, s[16:17]
	global_load_dwordx4 v[22:25], v[46:47], off
	global_load_dwordx4 v[26:29], v[14:15], off offset:16
	s_mov_b64 s[16:17], 0x6000
	v_addc_co_u32_e32 v49, vcc, 0, v103, vcc
	v_lshl_add_u64 v[14:15], v[102:103], 0, s[16:17]
	global_load_dwordx4 v[30:33], v[48:49], off
	global_load_dwordx4 v[34:37], v[14:15], off offset:16
	s_mov_b64 s[16:17], 0x6080
	v_and_b32_e32 v15, 48, v1
	v_lshl_add_u64 v[0:1], v[102:103], 0, s[16:17]
	s_mov_b64 s[16:17], 0x4080
	v_or_b32_e32 v14, s0, v99
	s_movk_i32 s1, 0x110
	s_movk_i32 s95, 0x6000
	s_waitcnt vmcnt(7)
	v_cvt_pk_bf16_f32 v40, v2, v3
	s_waitcnt vmcnt(6)
	v_cvt_pk_bf16_f32 v38, v6, v7
	s_waitcnt vmcnt(4)
	v_cvt_pk_bf16_f32 v44, v18, v19
	v_cvt_pk_bf16_f32 v45, v20, v21
	s_waitcnt vmcnt(3)
	v_cvt_pk_bf16_f32 v18, v22, v23
	s_waitcnt vmcnt(2)
	v_cvt_pk_bf16_f32 v20, v26, v27
	v_cvt_pk_bf16_f32 v21, v28, v29
	v_cvt_pk_bf16_f32 v19, v24, v25
	s_waitcnt vmcnt(1)
	v_cvt_pk_bf16_f32 v22, v30, v31
	v_cvt_pk_bf16_f32 v23, v32, v33
	global_load_dwordx4 v[26:29], v[48:49], off offset:128
	global_load_dwordx4 v[30:33], v[0:1], off offset:16
	v_lshl_add_u64 v[0:1], v[102:103], 0, s[16:17]
	s_mov_b64 s[16:17], 0x2080
	s_waitcnt vmcnt(2)
	v_cvt_pk_bf16_f32 v24, v34, v35
	v_cvt_pk_bf16_f32 v25, v36, v37
	global_load_dwordx4 v[34:37], v[46:47], off offset:128
	s_nop 0
	global_load_dwordx4 v[46:49], v[0:1], off offset:16
	v_lshl_add_u64 v[0:1], v[102:103], 0, s[16:17]
	global_load_dwordx4 v[50:53], v[50:51], off offset:128
	s_nop 0
	global_load_dwordx4 v[54:57], v[0:1], off offset:16
	global_load_dwordx4 v[58:61], v16, s[4:5] offset:144
	global_load_dwordx4 v[62:65], v16, s[4:5] offset:128
	v_mul_lo_u32 v0, v14, s1
	v_add3_u32 v112, 0, v15, v0
	v_cvt_pk_bf16_f32 v39, v8, v9
	v_cvt_pk_bf16_f32 v41, v4, v5
	v_cvt_pk_bf16_f32 v42, v10, v11
	v_cvt_pk_bf16_f32 v43, v12, v13
	ds_read_b128 v[0:3], v112
	ds_read_b128 v[4:7], v112 offset:4352
	ds_read_b128 v[8:11], v112 offset:8704
	ds_read_b128 v[12:15], v112 offset:13056
	s_waitcnt lgkmcnt(3)
	v_mfma_f32_16x16x32_bf16 v[66:69], v[38:41], v[0:3], 0
	s_and_b32 s1, s12, 0xffffff80
	v_mul_u32_u24_e32 v16, 0x7000, v98
	v_lshl_or_b32 v98, v98, 2, s1
	s_waitcnt lgkmcnt(1)
	v_mfma_f32_16x16x32_bf16 v[108:111], v[42:45], v[8:11], 0
	v_readlane_b32 s4, v255, 24
	v_or_b32_e32 v16, v16, v99
	v_ashrrev_i32_e32 v99, 31, v98
	v_mfma_f32_16x16x32_bf16 v[114:117], v[18:21], v[0:3], 0
	v_readlane_b32 s5, v255, 25
	s_ashr_i32 s1, s0, 31
	s_lshl_b64 s[0:1], s[0:1], 1
	v_mfma_f32_16x16x32_bf16 v[118:121], v[18:21], v[4:7], 0
	s_add_u32 s0, s2, s0
	v_lshlrev_b32_e32 v16, 1, v16
	s_addc_u32 s1, s13, s1
	v_mfma_f32_16x16x32_bf16 v[122:125], v[18:21], v[8:11], 0
	s_waitcnt vmcnt(7)
	v_cvt_pk_bf16_f32 v146, v26, v27
	s_waitcnt lgkmcnt(0)
	v_mfma_f32_16x16x32_bf16 v[126:129], v[18:21], v[12:15], 0
	v_cvt_pk_bf16_f32 v147, v28, v29
	s_waitcnt vmcnt(6)
	v_cvt_pk_bf16_f32 v148, v30, v31
	v_cvt_pk_bf16_f32 v149, v32, v33
	s_waitcnt vmcnt(5)
	v_cvt_pk_bf16_f32 v34, v34, v35
	v_cvt_pk_bf16_f32 v35, v36, v37
	s_waitcnt vmcnt(4)
	v_cvt_pk_bf16_f32 v36, v46, v47
	v_cvt_pk_bf16_f32 v37, v48, v49
	s_waitcnt vmcnt(3)
	v_cvt_pk_bf16_f32 v46, v50, v51
	v_cvt_pk_bf16_f32 v47, v52, v53
	s_waitcnt vmcnt(2)
	v_cvt_pk_bf16_f32 v48, v54, v55
	v_cvt_pk_bf16_f32 v49, v56, v57
	s_waitcnt vmcnt(0)
	v_cvt_pk_bf16_f32 v50, v62, v63
	v_cvt_pk_bf16_f32 v51, v64, v65
	v_cvt_pk_bf16_f32 v52, v58, v59
	v_cvt_pk_bf16_f32 v53, v60, v61
	v_mfma_f32_16x16x32_bf16 v[130:133], v[22:25], v[0:3], 0
	v_mfma_f32_16x16x32_bf16 v[134:137], v[22:25], v[4:7], 0
	v_mfma_f32_16x16x32_bf16 v[138:141], v[22:25], v[8:11], 0
	v_mfma_f32_16x16x32_bf16 v[142:145], v[22:25], v[12:15], 0
	ds_read_b128 v[18:21], v112 offset:64
	ds_read_b128 v[22:25], v112 offset:4416
	ds_read_b128 v[26:29], v112 offset:8768
	ds_read_b128 v[30:33], v112 offset:13120
	s_waitcnt lgkmcnt(3)
	v_mfma_f32_16x16x32_bf16 v[94:97], v[50:53], v[18:21], v[66:69]
	s_waitcnt lgkmcnt(1)
	v_mfma_f32_16x16x32_bf16 v[66:69], v[46:49], v[26:29], v[108:111]
	s_nop 2
	v_lshl_add_u64 v[108:109], v[98:99], 2, s[4:5]
	global_load_dwordx4 v[98:101], v[108:109], off
	global_load_dwordx4 v[188:191], v[108:109], off offset:64
	global_load_dwordx4 v[192:195], v[108:109], off offset:128
	global_load_dwordx4 v[196:199], v[108:109], off offset:192
	global_load_dwordx4 v[200:203], v[108:109], off offset:256
	global_load_dwordx4 v[204:207], v[108:109], off offset:320
	global_load_dwordx4 v[208:211], v[108:109], off offset:384
	global_load_dwordx4 v[212:215], v[108:109], off offset:448
	v_mfma_f32_16x16x32_bf16 v[70:73], v[38:41], v[4:7], 0
	v_mfma_f32_16x16x32_bf16 v[104:107], v[42:45], v[4:7], 0
	v_mfma_f32_16x16x32_bf16 v[74:77], v[38:41], v[8:11], 0
	v_mfma_f32_16x16x32_bf16 v[38:41], v[38:41], v[12:15], 0
	v_mfma_f32_16x16x32_bf16 v[86:89], v[50:53], v[22:25], v[70:73]
	v_mfma_f32_16x16x32_bf16 v[70:73], v[46:49], v[22:25], v[104:107]
	s_nop 3
	v_lshl_add_u64 v[106:107], s[0:1], 0, v[16:17]
	v_mfma_f32_16x16x32_bf16 v[82:85], v[50:53], v[26:29], v[74:77]
	v_add_co_u32_e32 v110, vcc, s77, v106
	v_lshl_add_u64 v[104:105], v[106:107], 0, s[66:67]
	s_nop 0
	v_addc_co_u32_e32 v111, vcc, 0, v107, vcc
	s_waitcnt lgkmcnt(0)
	v_mfma_f32_16x16x32_bf16 v[90:93], v[50:53], v[30:33], v[38:41]
	s_waitcnt vmcnt(0)
	v_add_f32_e32 v16, v94, v98
	v_cvt_pk_bf16_f32 v16, v16, s0
	global_store_short v[110:111], v16, off offset:2560
	v_add_f32_e32 v16, v86, v98
	v_cvt_pk_bf16_f32 v16, v16, s0
	global_store_short v[104:105], v16, off offset:32
	v_add_f32_e32 v16, v82, v98
	v_cvt_pk_bf16_f32 v16, v16, s0
	global_store_short v[104:105], v16, off offset:64
	v_add_f32_e32 v16, v90, v98
	v_cvt_pk_bf16_f32 v16, v16, s0
	global_store_short v[104:105], v16, off offset:96
	s_mov_b64 s[0:1], 0x6200
	v_add_f32_e32 v16, v95, v99
	v_add_co_u32_e32 v94, vcc, s10, v106
	v_cvt_pk_bf16_f32 v16, v16, s0
	s_nop 0
	v_addc_co_u32_e32 v95, vcc, 0, v107, vcc
	global_store_short v[94:95], v16, off offset:512
	v_add_f32_e32 v16, v87, v99
	v_lshl_add_u64 v[104:105], v[106:107], 0, s[0:1]
	v_cvt_pk_bf16_f32 v16, v16, s0
	global_store_short v[104:105], v16, off offset:32
	v_add_f32_e32 v16, v83, v99
	v_cvt_pk_bf16_f32 v16, v16, s0
	global_store_short v[104:105], v16, off offset:64
	v_add_f32_e32 v16, v91, v99
	v_cvt_pk_bf16_f32 v16, v16, s0
	global_store_short v[104:105], v16, off offset:96
	s_mov_b64 s[0:1], 0x9a00
	v_add_f32_e32 v16, v96, v100
	v_lshl_add_u64 v[82:83], v[106:107], 0, s[0:1]
	v_cvt_pk_bf16_f32 v16, v16, s0
	s_mov_b32 s0, 0x9000
	v_add_co_u32_e32 v86, vcc, s0, v106
	v_mfma_f32_16x16x32_bf16 v[78:81], v[42:45], v[0:3], 0
	s_nop 0
	v_addc_co_u32_e32 v87, vcc, 0, v107, vcc
	global_store_short v[86:87], v16, off offset:2560
	v_add_f32_e32 v16, v88, v100
	v_cvt_pk_bf16_f32 v16, v16, s0
	global_store_short v[82:83], v16, off offset:32
	v_add_f32_e32 v16, v84, v100
	v_cvt_pk_bf16_f32 v16, v16, s0
	global_store_short v[82:83], v16, off offset:64
	v_add_f32_e32 v16, v92, v100
	v_cvt_pk_bf16_f32 v16, v16, s0
	global_store_short v[82:83], v16, off offset:96
	s_mov_b64 s[0:1], 0xd200
	v_add_f32_e32 v16, v97, v101
	v_lshl_add_u64 v[82:83], v[106:107], 0, s[0:1]
	v_cvt_pk_bf16_f32 v16, v16, s0
	s_mov_b32 s0, 0xd000
	v_add_co_u32_e32 v86, vcc, s0, v106
	v_mfma_f32_16x16x32_bf16 v[78:81], v[46:49], v[18:21], v[78:81]
	s_nop 0
	v_addc_co_u32_e32 v87, vcc, 0, v107, vcc
	global_store_short v[86:87], v16, off offset:512
	v_add_f32_e32 v16, v89, v101
	v_cvt_pk_bf16_f32 v16, v16, s0
	global_store_short v[82:83], v16, off offset:32
	v_add_f32_e32 v16, v85, v101
	v_cvt_pk_bf16_f32 v16, v16, s0
	global_store_short v[82:83], v16, off offset:64
	v_add_f32_e32 v16, v93, v101
	v_cvt_pk_bf16_f32 v16, v16, s0
	global_store_short v[82:83], v16, off offset:96
	v_mov_b32_e32 v82, v188
	v_mov_b32_e32 v83, v189
	v_mov_b32_e32 v84, v190
	v_mov_b32_e32 v85, v191
	v_mfma_f32_16x16x32_bf16 v[42:45], v[42:45], v[12:15], 0
	s_mov_b64 s[0:1], 0x3aa00
	v_lshl_add_u64 v[86:87], v[106:107], 0, s[0:1]
	v_add_f32_e32 v16, v78, v82
	v_cvt_pk_bf16_f32 v16, v16, s0
	s_mov_b32 s0, 0x3a000
	v_add_co_u32_e32 v88, vcc, s0, v106
	v_mfma_f32_16x16x32_bf16 v[74:77], v[46:49], v[30:33], v[42:45]
	s_nop 0
	v_addc_co_u32_e32 v89, vcc, 0, v107, vcc
	global_store_short v[88:89], v16, off offset:2560
	v_add_f32_e32 v16, v70, v82
	v_cvt_pk_bf16_f32 v16, v16, s0
	global_store_short v[86:87], v16, off offset:32
	v_add_f32_e32 v16, v66, v82
	v_cvt_pk_bf16_f32 v16, v16, s0
	global_store_short v[86:87], v16, off offset:64
	v_add_f32_e32 v16, v74, v82
	v_cvt_pk_bf16_f32 v16, v16, s0
	global_store_short v[86:87], v16, off offset:96
	s_mov_b64 s[0:1], 0x3e200
	v_add_f32_e32 v16, v79, v83
	v_lshl_add_u64 v[86:87], v[106:107], 0, s[0:1]
	v_cvt_pk_bf16_f32 v16, v16, s0
	s_mov_b32 s0, 0x3e000
	v_add_co_u32_e32 v78, vcc, s0, v106
	v_mfma_f32_16x16x32_bf16 v[62:65], v[34:37], v[18:21], v[114:117]
	s_nop 0
	v_addc_co_u32_e32 v79, vcc, 0, v107, vcc
	global_store_short v[78:79], v16, off offset:512
	v_add_f32_e32 v16, v71, v83
	v_cvt_pk_bf16_f32 v16, v16, s0
	global_store_short v[86:87], v16, off offset:32
	v_add_f32_e32 v16, v67, v83
	v_cvt_pk_bf16_f32 v16, v16, s0
	global_store_short v[86:87], v16, off offset:64
	v_add_f32_e32 v16, v75, v83
	v_cvt_pk_bf16_f32 v16, v16, s0
	global_store_short v[86:87], v16, off offset:96
	s_mov_b64 s[0:1], 0x41a00
	v_add_f32_e32 v16, v80, v84
	v_lshl_add_u64 v[66:67], v[106:107], 0, s[0:1]
	v_cvt_pk_bf16_f32 v16, v16, s0
	s_mov_b32 s0, 0x41000
	v_add_co_u32_e32 v70, vcc, s0, v106
	v_mfma_f32_16x16x32_bf16 v[54:57], v[34:37], v[22:25], v[118:121]
	s_nop 0
	v_addc_co_u32_e32 v71, vcc, 0, v107, vcc
	global_store_short v[70:71], v16, off offset:2560
	v_add_f32_e32 v16, v72, v84
	v_cvt_pk_bf16_f32 v16, v16, s0
	global_store_short v[66:67], v16, off offset:32
	v_add_f32_e32 v16, v68, v84
	v_cvt_pk_bf16_f32 v16, v16, s0
	global_store_short v[66:67], v16, off offset:64
	v_add_f32_e32 v16, v76, v84
	v_cvt_pk_bf16_f32 v16, v16, s0
	global_store_short v[66:67], v16, off offset:96
	s_mov_b64 s[0:1], 0x45200
	v_add_f32_e32 v16, v81, v85
	v_lshl_add_u64 v[66:67], v[106:107], 0, s[0:1]
	v_cvt_pk_bf16_f32 v16, v16, s0
	s_mov_b32 s0, 0x45000
	v_add_co_u32_e32 v70, vcc, s0, v106
	v_mfma_f32_16x16x32_bf16 v[50:53], v[34:37], v[26:29], v[122:125]
	s_nop 0
	v_addc_co_u32_e32 v71, vcc, 0, v107, vcc
	global_store_short v[70:71], v16, off offset:512
	v_add_f32_e32 v16, v73, v85
	v_cvt_pk_bf16_f32 v16, v16, s0
	global_store_short v[66:67], v16, off offset:32
	v_add_f32_e32 v16, v69, v85
	v_cvt_pk_bf16_f32 v16, v16, s0
	global_store_short v[66:67], v16, off offset:64
	v_add_f32_e32 v16, v77, v85
	v_cvt_pk_bf16_f32 v16, v16, s0
	global_store_short v[66:67], v16, off offset:96
	v_mov_b32_e32 v66, v192
	v_mov_b32_e32 v67, v193
	v_mov_b32_e32 v68, v194
	v_mov_b32_e32 v69, v195
	s_mov_b64 s[0:1], 0x72a00
	v_lshl_add_u64 v[70:71], v[106:107], 0, s[0:1]
	v_mfma_f32_16x16x32_bf16 v[58:61], v[34:37], v[30:33], v[126:129]
	v_add_f32_e32 v16, v62, v66
	v_cvt_pk_bf16_f32 v16, v16, s0
	s_mov_b32 s0, 0x72000
	v_add_co_u32_e32 v72, vcc, s0, v106
	v_mfma_f32_16x16x32_bf16 v[46:49], v[146:149], v[18:21], v[130:133]
	s_nop 0
	v_addc_co_u32_e32 v73, vcc, 0, v107, vcc
	global_store_short v[72:73], v16, off offset:2560
	v_add_f32_e32 v16, v54, v66
	v_cvt_pk_bf16_f32 v16, v16, s0
	global_store_short v[70:71], v16, off offset:32
	v_add_f32_e32 v16, v50, v66
	v_cvt_pk_bf16_f32 v16, v16, s0
	global_store_short v[70:71], v16, off offset:64
	v_add_f32_e32 v16, v58, v66
	v_cvt_pk_bf16_f32 v16, v16, s0
	global_store_short v[70:71], v16, off offset:96
	s_mov_b64 s[0:1], 0x76200
	v_add_f32_e32 v16, v63, v67
	v_lshl_add_u64 v[70:71], v[106:107], 0, s[0:1]
	v_cvt_pk_bf16_f32 v16, v16, s0
	s_mov_b32 s0, 0x76000
	v_add_co_u32_e32 v62, vcc, s0, v106
	v_mfma_f32_16x16x32_bf16 v[42:45], v[146:149], v[22:25], v[134:137]
	s_nop 0
	v_addc_co_u32_e32 v63, vcc, 0, v107, vcc
	global_store_short v[62:63], v16, off offset:512
	v_add_f32_e32 v16, v55, v67
	v_cvt_pk_bf16_f32 v16, v16, s0
	global_store_short v[70:71], v16, off offset:32
	v_add_f32_e32 v16, v51, v67
	v_cvt_pk_bf16_f32 v16, v16, s0
	global_store_short v[70:71], v16, off offset:64
	v_add_f32_e32 v16, v59, v67
	v_cvt_pk_bf16_f32 v16, v16, s0
	global_store_short v[70:71], v16, off offset:96
	s_mov_b64 s[0:1], 0x79a00
	v_add_f32_e32 v16, v64, v68
	v_lshl_add_u64 v[50:51], v[106:107], 0, s[0:1]
	v_cvt_pk_bf16_f32 v16, v16, s0
	s_mov_b32 s0, 0x79000
	v_add_co_u32_e32 v54, vcc, s0, v106
	v_mfma_f32_16x16x32_bf16 v[38:41], v[146:149], v[26:29], v[138:141]
	s_nop 0
	v_addc_co_u32_e32 v55, vcc, 0, v107, vcc
	global_store_short v[54:55], v16, off offset:2560
	v_add_f32_e32 v16, v56, v68
	v_cvt_pk_bf16_f32 v16, v16, s0
	global_store_short v[50:51], v16, off offset:32
	v_add_f32_e32 v16, v52, v68
	v_cvt_pk_bf16_f32 v16, v16, s0
	global_store_short v[50:51], v16, off offset:64
	v_add_f32_e32 v16, v60, v68
	v_cvt_pk_bf16_f32 v16, v16, s0
	global_store_short v[50:51], v16, off offset:96
	s_mov_b64 s[0:1], 0x7d200
	v_add_f32_e32 v16, v65, v69
	v_lshl_add_u64 v[50:51], v[106:107], 0, s[0:1]
	v_cvt_pk_bf16_f32 v16, v16, s0
	s_mov_b32 s0, 0x7d000
	v_add_co_u32_e32 v54, vcc, s0, v106
	v_mfma_f32_16x16x32_bf16 v[34:37], v[146:149], v[30:33], v[142:145]
	s_nop 0
	v_addc_co_u32_e32 v55, vcc, 0, v107, vcc
	global_store_short v[54:55], v16, off offset:512
	v_add_f32_e32 v16, v57, v69
	v_cvt_pk_bf16_f32 v16, v16, s0
	global_store_short v[50:51], v16, off offset:32
	v_add_f32_e32 v16, v53, v69
	v_cvt_pk_bf16_f32 v16, v16, s0
	global_store_short v[50:51], v16, off offset:64
	v_add_f32_e32 v16, v61, v69
	v_cvt_pk_bf16_f32 v16, v16, s0
	global_store_short v[50:51], v16, off offset:96
	v_mov_b32_e32 v50, v196
	v_mov_b32_e32 v51, v197
	v_mov_b32_e32 v52, v198
	v_mov_b32_e32 v53, v199
	s_mov_b64 s[0:1], 0xaaa00
	v_lshl_add_u64 v[54:55], v[106:107], 0, s[0:1]
	v_add_f32_e32 v16, v46, v50
	v_cvt_pk_bf16_f32 v16, v16, s0
	s_mov_b32 s0, 0xaa000
	v_add_co_u32_e32 v56, vcc, s0, v106
	s_nop 1
	v_addc_co_u32_e32 v57, vcc, 0, v107, vcc
	global_store_short v[56:57], v16, off offset:2560
	v_add_f32_e32 v16, v42, v50
	v_cvt_pk_bf16_f32 v16, v16, s0
	global_store_short v[54:55], v16, off offset:32
	v_add_f32_e32 v16, v38, v50
	v_cvt_pk_bf16_f32 v16, v16, s0
	global_store_short v[54:55], v16, off offset:64
	v_add_f32_e32 v16, v34, v50
	v_cvt_pk_bf16_f32 v16, v16, s0
	global_store_short v[54:55], v16, off offset:96
	s_mov_b64 s[0:1], 0xae200
	v_add_f32_e32 v16, v47, v51
	v_lshl_add_u64 v[54:55], v[106:107], 0, s[0:1]
	v_cvt_pk_bf16_f32 v16, v16, s0
	s_mov_b32 s0, 0xae000
	v_add_co_u32_e32 v46, vcc, s0, v106
	s_nop 1
	v_addc_co_u32_e32 v47, vcc, 0, v107, vcc
	global_store_short v[46:47], v16, off offset:512
	v_add_f32_e32 v16, v43, v51
	v_cvt_pk_bf16_f32 v16, v16, s0
	global_store_short v[54:55], v16, off offset:32
	v_add_f32_e32 v16, v39, v51
	v_cvt_pk_bf16_f32 v16, v16, s0
	global_store_short v[54:55], v16, off offset:64
	v_add_f32_e32 v16, v35, v51
	v_cvt_pk_bf16_f32 v16, v16, s0
	global_store_short v[54:55], v16, off offset:96
	s_mov_b64 s[0:1], 0xb1a00
	v_add_f32_e32 v16, v48, v52
	v_lshl_add_u64 v[34:35], v[106:107], 0, s[0:1]
	v_cvt_pk_bf16_f32 v16, v16, s0
	s_mov_b32 s0, 0xb1000
	v_add_co_u32_e32 v38, vcc, s0, v106
	s_nop 1
	v_addc_co_u32_e32 v39, vcc, 0, v107, vcc
	global_store_short v[38:39], v16, off offset:2560
	v_add_f32_e32 v16, v44, v52
	v_cvt_pk_bf16_f32 v16, v16, s0
	global_store_short v[34:35], v16, off offset:32
	v_add_f32_e32 v16, v40, v52
	v_cvt_pk_bf16_f32 v16, v16, s0
	global_store_short v[34:35], v16, off offset:64
	v_add_f32_e32 v16, v36, v52
	v_cvt_pk_bf16_f32 v16, v16, s0
	global_store_short v[34:35], v16, off offset:96
	s_mov_b64 s[0:1], 0xb5200
	v_add_f32_e32 v16, v49, v53
	v_lshl_add_u64 v[34:35], v[106:107], 0, s[0:1]
	v_cvt_pk_bf16_f32 v16, v16, s0
	s_mov_b32 s0, 0xb5000
	v_add_co_u32_e32 v38, vcc, s0, v106
	s_nop 1
	v_addc_co_u32_e32 v39, vcc, 0, v107, vcc
	global_store_short v[38:39], v16, off offset:512
	v_add_f32_e32 v16, v45, v53
	v_cvt_pk_bf16_f32 v16, v16, s0
	global_store_short v[34:35], v16, off offset:32
	v_add_f32_e32 v16, v41, v53
	v_cvt_pk_bf16_f32 v16, v16, s0
	global_store_short v[34:35], v16, off offset:64
	v_add_f32_e32 v16, v37, v53
	v_cvt_pk_bf16_f32 v16, v16, s0
	s_mov_b64 s[0:1], 0x8000
	v_lshl_add_u64 v[110:111], v[102:103], 0, s[0:1]
	s_mov_b32 s0, 0x8000
	global_store_short v[34:35], v16, off offset:96
	v_add_co_u32_e32 v34, vcc, s0, v102
	s_mov_b64 s[0:1], 0xa000
	s_nop 0
	v_addc_co_u32_e32 v35, vcc, 0, v103, vcc
	v_lshl_add_u64 v[46:47], v[102:103], 0, s[0:1]
	v_add_co_u32_e32 v104, vcc, s61, v102
	s_mov_b64 s[0:1], 0xc000
	s_nop 0
	v_addc_co_u32_e32 v105, vcc, 0, v103, vcc
	v_lshl_add_u64 v[54:55], v[102:103], 0, s[0:1]
	s_mov_b32 s0, 0xc000
	v_add_co_u32_e32 v178, vcc, s0, v102
	s_mov_b64 s[0:1], 0xe000
	s_nop 0
	v_addc_co_u32_e32 v179, vcc, 0, v103, vcc
	v_add_co_u32_e32 v180, vcc, s51, v102
	global_load_dwordx4 v[34:37], v[34:35], off
	s_nop 0
	global_load_dwordx4 v[38:41], v[110:111], off offset:16
	global_load_dwordx4 v[42:45], v[104:105], off
	s_nop 0
	global_load_dwordx4 v[46:49], v[46:47], off offset:16
	s_nop 0
	global_load_dwordx4 v[50:53], v[178:179], off
	s_nop 0
	global_load_dwordx4 v[54:57], v[54:55], off offset:16
	v_lshl_add_u64 v[62:63], v[102:103], 0, s[0:1]
	v_addc_co_u32_e32 v181, vcc, 0, v103, vcc
	global_load_dwordx4 v[58:61], v[180:181], off
	s_nop 0
	global_load_dwordx4 v[62:65], v[62:63], off offset:16
	s_mov_b64 s[0:1], 0xe080
	s_waitcnt vmcnt(7)
	v_cvt_pk_bf16_f32 v34, v34, v35
	v_cvt_pk_bf16_f32 v35, v36, v37
	s_waitcnt vmcnt(6)
	v_cvt_pk_bf16_f32 v36, v38, v39
	s_waitcnt vmcnt(5)
	v_cvt_pk_bf16_f32 v39, v44, v45
	s_waitcnt vmcnt(2)
	v_cvt_pk_bf16_f32 v44, v54, v55
	v_lshl_add_u64 v[54:55], v[102:103], 0, s[0:1]
	s_mov_b64 s[0:1], 0xc080
	v_cvt_pk_bf16_f32 v37, v40, v41
	v_cvt_pk_bf16_f32 v41, v48, v49
	s_waitcnt vmcnt(0)
	v_cvt_pk_bf16_f32 v48, v62, v63
	v_lshl_add_u64 v[62:63], v[102:103], 0, s[0:1]
	s_mov_b64 s[0:1], 0xa080
	v_lshl_add_u64 v[70:71], v[102:103], 0, s[0:1]
	v_cvt_pk_bf16_f32 v38, v42, v43
	v_cvt_pk_bf16_f32 v40, v46, v47
	v_cvt_pk_bf16_f32 v42, v50, v51
	v_cvt_pk_bf16_f32 v43, v52, v53
	v_cvt_pk_bf16_f32 v45, v56, v57
	v_cvt_pk_bf16_f32 v46, v58, v59
	v_cvt_pk_bf16_f32 v47, v60, v61
	v_cvt_pk_bf16_f32 v49, v64, v65
	global_load_dwordx4 v[50:53], v[180:181], off offset:128
	s_nop 0
	global_load_dwordx4 v[54:57], v[54:55], off offset:16
	s_nop 0
	global_load_dwordx4 v[58:61], v[178:179], off offset:128
	s_nop 0
	global_load_dwordx4 v[62:65], v[62:63], off offset:16
	s_nop 0
	global_load_dwordx4 v[66:69], v[104:105], off offset:128
	s_nop 0
	global_load_dwordx4 v[70:73], v[70:71], off offset:16
	s_nop 0
	global_load_dwordx4 v[74:77], v[110:111], off offset:144
	global_load_dwordx4 v[78:81], v[110:111], off offset:128
	s_mov_b64 s[0:1], 0xe100
	v_mfma_f32_16x16x32_bf16 v[82:85], v[34:37], v[0:3], 0
	v_mfma_f32_16x16x32_bf16 v[86:89], v[34:37], v[4:7], 0
	v_mfma_f32_16x16x32_bf16 v[90:93], v[34:37], v[8:11], 0
	v_mfma_f32_16x16x32_bf16 v[34:37], v[34:37], v[12:15], 0
	v_mfma_f32_16x16x32_bf16 v[94:97], v[38:41], v[0:3], 0
	v_mfma_f32_16x16x32_bf16 v[118:121], v[38:41], v[12:15], 0
	v_mfma_f32_16x16x32_bf16 v[122:125], v[42:45], v[0:3], 0
	v_mfma_f32_16x16x32_bf16 v[134:137], v[42:45], v[12:15], 0
	v_mfma_f32_16x16x32_bf16 v[138:141], v[46:49], v[0:3], 0
	v_lshl_add_u64 v[0:1], v[102:103], 0, s[0:1]
	s_mov_b64 s[0:1], 0xc100
	global_load_dwordx4 v[154:157], v[180:181], off offset:256
	global_load_dwordx4 v[158:161], v[0:1], off offset:16
	v_mfma_f32_16x16x32_bf16 v[150:153], v[46:49], v[12:15], 0
	v_lshl_add_u64 v[0:1], v[102:103], 0, s[0:1]
	s_mov_b64 s[0:1], 0xa100
	global_load_dwordx4 v[162:165], v[178:179], off offset:256
	global_load_dwordx4 v[166:169], v[0:1], off offset:16
	v_mfma_f32_16x16x32_bf16 v[142:145], v[46:49], v[4:7], 0
	v_lshl_add_u64 v[0:1], v[102:103], 0, s[0:1]
	s_mov_b64 s[0:1], 0xe180
	s_waitcnt vmcnt(5)
	v_cvt_pk_bf16_f32 v14, v74, v75
	s_waitcnt vmcnt(4)
	v_cvt_pk_bf16_f32 v12, v78, v79
	v_cvt_pk_bf16_f32 v13, v80, v81
	v_cvt_pk_bf16_f32 v15, v76, v77
	v_mfma_f32_16x16x32_bf16 v[146:149], v[46:49], v[8:11], 0
	v_cvt_pk_bf16_f32 v46, v66, v67
	v_cvt_pk_bf16_f32 v47, v68, v69
	v_cvt_pk_bf16_f32 v48, v70, v71
	v_cvt_pk_bf16_f32 v49, v72, v73
	global_load_dwordx4 v[74:77], v[104:105], off offset:256
	global_load_dwordx4 v[170:173], v[0:1], off offset:16
	global_load_dwordx4 v[174:177], v[110:111], off offset:272
	global_load_dwordx4 v[78:81], v[110:111], off offset:256
	v_mfma_f32_16x16x32_bf16 v[98:101], v[38:41], v[4:7], 0
	v_cvt_pk_bf16_f32 v66, v58, v59
	v_cvt_pk_bf16_f32 v67, v60, v61
	v_cvt_pk_bf16_f32 v68, v62, v63
	v_mfma_f32_16x16x32_bf16 v[0:3], v[12:15], v[18:21], v[82:85]
	v_cvt_pk_bf16_f32 v69, v64, v65
	v_cvt_pk_bf16_f32 v70, v50, v51
	v_cvt_pk_bf16_f32 v71, v52, v53
	v_lshl_add_u64 v[82:83], v[102:103], 0, s[0:1]
	s_mov_b64 s[0:1], 0xc180
	v_mfma_f32_16x16x32_bf16 v[126:129], v[42:45], v[4:7], 0
	v_cvt_pk_bf16_f32 v72, v54, v55
	v_cvt_pk_bf16_f32 v73, v56, v57
	s_waitcnt vmcnt(3)
	v_cvt_pk_bf16_f32 v74, v74, v75
	v_mfma_f32_16x16x32_bf16 v[4:7], v[12:15], v[22:25], v[86:89]
	v_cvt_pk_bf16_f32 v75, v76, v77
	s_waitcnt vmcnt(0)
	v_cvt_pk_bf16_f32 v78, v78, v79
	v_cvt_pk_bf16_f32 v79, v80, v81
	v_lshl_add_u64 v[86:87], v[102:103], 0, s[0:1]
	v_mfma_f32_16x16x32_bf16 v[114:117], v[38:41], v[8:11], 0
	s_mov_b64 s[0:1], 0xa180
	v_cvt_pk_bf16_f32 v80, v174, v175
	v_cvt_pk_bf16_f32 v81, v176, v177
	v_mfma_f32_16x16x32_bf16 v[130:133], v[42:45], v[8:11], 0
	v_cvt_pk_bf16_f32 v76, v170, v171
	v_cvt_pk_bf16_f32 v77, v172, v173
	v_mfma_f32_16x16x32_bf16 v[8:11], v[12:15], v[26:29], v[90:93]
	v_mfma_f32_16x16x32_bf16 v[12:15], v[12:15], v[30:33], v[34:37]
	s_nop 1
	v_lshl_add_u64 v[90:91], v[102:103], 0, s[0:1]
	s_mov_b64 s[0:1], 0xe2a00
	v_mfma_f32_16x16x32_bf16 v[34:37], v[46:49], v[18:21], v[94:97]
	s_nop 2
	global_load_dwordx4 v[94:97], v[180:181], off offset:384
	s_nop 0
	global_load_dwordx4 v[82:85], v[82:83], off offset:16
	s_waitcnt vmcnt(1)
	v_cvt_pk_bf16_f32 v94, v94, v95
	v_mfma_f32_16x16x32_bf16 v[38:41], v[46:49], v[22:25], v[98:101]
	s_nop 2
	global_load_dwordx4 v[98:101], v[178:179], off offset:384
	s_nop 0
	global_load_dwordx4 v[86:89], v[86:87], off offset:16
	v_cvt_pk_bf16_f32 v95, v96, v97
	s_waitcnt vmcnt(2)
	v_cvt_pk_bf16_f32 v96, v82, v83
	v_mfma_f32_16x16x32_bf16 v[42:45], v[46:49], v[26:29], v[114:117]
	v_cvt_pk_bf16_f32 v97, v84, v85
	v_mfma_f32_16x16x32_bf16 v[46:49], v[46:49], v[30:33], v[118:121]
	global_load_dwordx4 v[102:105], v[104:105], off offset:384
	s_nop 0
	global_load_dwordx4 v[90:93], v[90:91], off offset:16
	s_nop 0
	global_load_dwordx4 v[114:117], v[110:111], off offset:400
	global_load_dwordx4 v[118:121], v[110:111], off offset:384
	v_mfma_f32_16x16x32_bf16 v[50:53], v[66:69], v[18:21], v[122:125]
	v_mfma_f32_16x16x32_bf16 v[54:57], v[66:69], v[22:25], v[126:129]
	v_mfma_f32_16x16x32_bf16 v[58:61], v[66:69], v[26:29], v[130:133]
	v_mfma_f32_16x16x32_bf16 v[62:65], v[66:69], v[30:33], v[134:137]
	v_cvt_pk_bf16_f32 v66, v154, v155
	v_cvt_pk_bf16_f32 v67, v156, v157
	v_cvt_pk_bf16_f32 v68, v158, v159
	v_cvt_pk_bf16_f32 v69, v160, v161
	ds_read_b128 v[122:125], v112 offset:128
	ds_read_b128 v[126:129], v112 offset:4480
	ds_read_b128 v[130:133], v112 offset:8832
	ds_read_b128 v[134:137], v112 offset:13184
	v_mfma_f32_16x16x32_bf16 v[18:21], v[70:73], v[18:21], v[138:141]
	v_mfma_f32_16x16x32_bf16 v[22:25], v[70:73], v[22:25], v[142:145]
	v_mfma_f32_16x16x32_bf16 v[26:29], v[70:73], v[26:29], v[146:149]
	v_mfma_f32_16x16x32_bf16 v[30:33], v[70:73], v[30:33], v[150:153]
	v_cvt_pk_bf16_f32 v70, v162, v163
	v_cvt_pk_bf16_f32 v71, v164, v165
	v_cvt_pk_bf16_f32 v72, v166, v167
	v_cvt_pk_bf16_f32 v73, v168, v169
	s_waitcnt lgkmcnt(3)
	v_mfma_f32_16x16x32_bf16 v[0:3], v[78:81], v[122:125], v[0:3]
	s_waitcnt lgkmcnt(2)
	v_mfma_f32_16x16x32_bf16 v[4:7], v[78:81], v[126:129], v[4:7]
	s_waitcnt lgkmcnt(1)
	v_mfma_f32_16x16x32_bf16 v[8:11], v[78:81], v[130:133], v[8:11]
	s_waitcnt lgkmcnt(0)
	v_mfma_f32_16x16x32_bf16 v[12:15], v[78:81], v[134:137], v[12:15]
	v_mfma_f32_16x16x32_bf16 v[78:81], v[66:69], v[126:129], v[22:25]
	v_mfma_f32_16x16x32_bf16 v[50:53], v[70:73], v[122:125], v[50:53]
	s_waitcnt vmcnt(5)
	s_nop 0
	v_cvt_pk_bf16_f32 v22, v98, v99
	v_cvt_pk_bf16_f32 v23, v100, v101
	s_waitcnt vmcnt(4)
	v_cvt_pk_bf16_f32 v24, v86, v87
	v_cvt_pk_bf16_f32 v25, v88, v89
	v_mfma_f32_16x16x32_bf16 v[54:57], v[70:73], v[126:129], v[54:57]
	v_mfma_f32_16x16x32_bf16 v[58:61], v[70:73], v[130:133], v[58:61]
	v_mfma_f32_16x16x32_bf16 v[62:65], v[70:73], v[134:137], v[62:65]
	v_mfma_f32_16x16x32_bf16 v[70:73], v[66:69], v[122:125], v[18:21]
	s_waitcnt vmcnt(2)
	s_nop 1
	v_cvt_pk_bf16_f32 v20, v90, v91
	v_cvt_pk_bf16_f32 v21, v92, v93
	ds_read_b128 v[82:85], v112 offset:192
	ds_read_b128 v[86:89], v112 offset:4544
	ds_read_b128 v[90:93], v112 offset:8896
	ds_read_b128 v[98:101], v112 offset:13248
	v_mfma_f32_16x16x32_bf16 v[34:37], v[74:77], v[122:125], v[34:37]
	v_cvt_pk_bf16_f32 v18, v102, v103
	v_cvt_pk_bf16_f32 v19, v104, v105
	v_mfma_f32_16x16x32_bf16 v[122:125], v[66:69], v[130:133], v[26:29]
	v_mfma_f32_16x16x32_bf16 v[66:69], v[66:69], v[134:137], v[30:33]
	s_waitcnt vmcnt(0)
	s_nop 0
	v_cvt_pk_bf16_f32 v26, v118, v119
	v_cvt_pk_bf16_f32 v27, v120, v121
	v_cvt_pk_bf16_f32 v28, v114, v115
	s_waitcnt lgkmcnt(3)
	v_mfma_f32_16x16x32_bf16 v[30:33], v[22:25], v[82:85], v[50:53]
	v_cvt_pk_bf16_f32 v29, v116, v117
	s_nop 1
	v_mov_b32_e32 v50, v200
	v_mov_b32_e32 v51, v201
	v_mov_b32_e32 v52, v202
	v_mov_b32_e32 v53, v203
	v_mfma_f32_16x16x32_bf16 v[102:105], v[26:29], v[82:85], v[0:3]
	s_waitcnt lgkmcnt(2)
	v_mfma_f32_16x16x32_bf16 v[110:113], v[26:29], v[86:89], v[4:7]
	s_nop 4
	v_add_f32_e32 v16, v102, v50
	s_waitcnt lgkmcnt(1)
	v_mfma_f32_16x16x32_bf16 v[114:117], v[26:29], v[90:93], v[8:11]
	v_cvt_pk_bf16_f32 v16, v16, s0
	s_waitcnt lgkmcnt(0)
	v_mfma_f32_16x16x32_bf16 v[118:121], v[26:29], v[98:101], v[12:15]
	v_mfma_f32_16x16x32_bf16 v[26:29], v[22:25], v[86:89], v[54:57]
	s_nop 2
	v_lshl_add_u64 v[54:55], v[106:107], 0, s[0:1]
	s_mov_b32 s0, 0xe2000
	v_add_co_u32_e32 v56, vcc, s0, v106
	v_mfma_f32_16x16x32_bf16 v[38:41], v[74:77], v[126:129], v[38:41]
	s_nop 0
	v_addc_co_u32_e32 v57, vcc, 0, v107, vcc
	global_store_short v[56:57], v16, off offset:2560
	v_add_f32_e32 v16, v110, v50
	v_cvt_pk_bf16_f32 v16, v16, s0
	global_store_short v[54:55], v16, off offset:32
	v_add_f32_e32 v16, v114, v50
	v_cvt_pk_bf16_f32 v16, v16, s0
	global_store_short v[54:55], v16, off offset:64
	v_add_f32_e32 v16, v118, v50
	v_cvt_pk_bf16_f32 v16, v16, s0
	global_store_short v[54:55], v16, off offset:96
	s_mov_b64 s[0:1], 0xe6200
	v_add_f32_e32 v16, v103, v51
	v_lshl_add_u64 v[54:55], v[106:107], 0, s[0:1]
	v_cvt_pk_bf16_f32 v16, v16, s0
	s_mov_b32 s0, 0xe6000
	v_add_co_u32_e32 v56, vcc, s0, v106
	v_mfma_f32_16x16x32_bf16 v[42:45], v[74:77], v[130:133], v[42:45]
	s_nop 0
	v_addc_co_u32_e32 v57, vcc, 0, v107, vcc
	global_store_short v[56:57], v16, off offset:512
	v_add_f32_e32 v16, v111, v51
	v_cvt_pk_bf16_f32 v16, v16, s0
	global_store_short v[54:55], v16, off offset:32
	v_add_f32_e32 v16, v115, v51
	v_cvt_pk_bf16_f32 v16, v16, s0
	global_store_short v[54:55], v16, off offset:64
	v_add_f32_e32 v16, v119, v51
	v_cvt_pk_bf16_f32 v16, v16, s0
	global_store_short v[54:55], v16, off offset:96
	s_mov_b64 s[0:1], 0xe9a00
	v_add_f32_e32 v16, v104, v52
	v_lshl_add_u64 v[50:51], v[106:107], 0, s[0:1]
	v_cvt_pk_bf16_f32 v16, v16, s0
	s_mov_b32 s0, 0xe9000
	v_add_co_u32_e32 v54, vcc, s0, v106
	v_mfma_f32_16x16x32_bf16 v[74:77], v[74:77], v[134:137], v[46:49]
	s_nop 0
	v_addc_co_u32_e32 v55, vcc, 0, v107, vcc
	global_store_short v[54:55], v16, off offset:2560
	v_add_f32_e32 v16, v112, v52
	v_cvt_pk_bf16_f32 v16, v16, s0
	global_store_short v[50:51], v16, off offset:32
	v_add_f32_e32 v16, v116, v52
	v_cvt_pk_bf16_f32 v16, v16, s0
	global_store_short v[50:51], v16, off offset:64
	v_add_f32_e32 v16, v120, v52
	v_cvt_pk_bf16_f32 v16, v16, s0
	global_store_short v[50:51], v16, off offset:96
	s_mov_b64 s[0:1], 0xed200
	v_add_f32_e32 v16, v105, v53
	v_lshl_add_u64 v[50:51], v[106:107], 0, s[0:1]
	v_cvt_pk_bf16_f32 v16, v16, s0
	s_mov_b32 s0, 0xed000
	v_add_co_u32_e32 v54, vcc, s0, v106
	v_mfma_f32_16x16x32_bf16 v[46:49], v[18:21], v[82:85], v[34:37]
	s_nop 0
	v_addc_co_u32_e32 v55, vcc, 0, v107, vcc
	global_store_short v[54:55], v16, off offset:512
	v_add_f32_e32 v16, v113, v53
	v_cvt_pk_bf16_f32 v16, v16, s0
	global_store_short v[50:51], v16, off offset:32
	v_add_f32_e32 v16, v117, v53
	v_cvt_pk_bf16_f32 v16, v16, s0
	global_store_short v[50:51], v16, off offset:64
	v_add_f32_e32 v16, v121, v53
	v_cvt_pk_bf16_f32 v16, v16, s0
	global_store_short v[50:51], v16, off offset:96
	v_mov_b32_e32 v50, v204
	v_mov_b32_e32 v51, v205
	v_mov_b32_e32 v52, v206
	v_mov_b32_e32 v53, v207
	v_mfma_f32_16x16x32_bf16 v[38:41], v[18:21], v[86:89], v[38:41]
	s_mov_b64 s[0:1], 0x11aa00
	v_lshl_add_u64 v[54:55], v[106:107], 0, s[0:1]
	v_add_f32_e32 v16, v46, v50
	v_cvt_pk_bf16_f32 v16, v16, s0
	s_mov_b32 s0, 0x11a000
	v_mfma_f32_16x16x32_bf16 v[34:37], v[18:21], v[90:93], v[42:45]
	v_add_co_u32_e32 v56, vcc, s0, v106
	s_nop 1
	v_addc_co_u32_e32 v57, vcc, 0, v107, vcc
	v_mfma_f32_16x16x32_bf16 v[42:45], v[18:21], v[98:101], v[74:77]
	global_store_short v[56:57], v16, off offset:2560
	v_add_f32_e32 v16, v38, v50
	v_cvt_pk_bf16_f32 v16, v16, s0
	global_store_short v[54:55], v16, off offset:32
	v_add_f32_e32 v16, v34, v50
	v_cvt_pk_bf16_f32 v16, v16, s0
	global_store_short v[54:55], v16, off offset:64
	s_nop 0
	v_add_f32_e32 v16, v42, v50
	v_cvt_pk_bf16_f32 v16, v16, s0
	global_store_short v[54:55], v16, off offset:96
	s_mov_b64 s[0:1], 0x11e200
	v_add_f32_e32 v16, v47, v51
	v_lshl_add_u64 v[54:55], v[106:107], 0, s[0:1]
	v_cvt_pk_bf16_f32 v16, v16, s0
	s_mov_b32 s0, 0x11e000
	v_add_co_u32_e32 v46, vcc, s0, v106
	v_mfma_f32_16x16x32_bf16 v[18:21], v[22:25], v[90:93], v[58:61]
	s_nop 0
	v_addc_co_u32_e32 v47, vcc, 0, v107, vcc
	global_store_short v[46:47], v16, off offset:512
	v_add_f32_e32 v16, v39, v51
	v_cvt_pk_bf16_f32 v16, v16, s0
	global_store_short v[54:55], v16, off offset:32
	v_add_f32_e32 v16, v35, v51
	v_cvt_pk_bf16_f32 v16, v16, s0
	global_store_short v[54:55], v16, off offset:64
	v_add_f32_e32 v16, v43, v51
	v_cvt_pk_bf16_f32 v16, v16, s0
	global_store_short v[54:55], v16, off offset:96
	s_mov_b64 s[0:1], 0x121a00
	v_add_f32_e32 v16, v48, v52
	v_lshl_add_u64 v[34:35], v[106:107], 0, s[0:1]
	v_cvt_pk_bf16_f32 v16, v16, s0
	s_mov_b32 s0, 0x121000
	v_add_co_u32_e32 v38, vcc, s0, v106
	v_mfma_f32_16x16x32_bf16 v[22:25], v[22:25], v[98:101], v[62:65]
	s_nop 0
	v_addc_co_u32_e32 v39, vcc, 0, v107, vcc
	global_store_short v[38:39], v16, off offset:2560
	v_add_f32_e32 v16, v40, v52
	v_cvt_pk_bf16_f32 v16, v16, s0
	global_store_short v[34:35], v16, off offset:32
	v_add_f32_e32 v16, v36, v52
	v_cvt_pk_bf16_f32 v16, v16, s0
	global_store_short v[34:35], v16, off offset:64
	v_add_f32_e32 v16, v44, v52
	v_cvt_pk_bf16_f32 v16, v16, s0
	global_store_short v[34:35], v16, off offset:96
	s_mov_b64 s[0:1], 0x125200
	v_add_f32_e32 v16, v49, v53
	v_lshl_add_u64 v[34:35], v[106:107], 0, s[0:1]
	v_cvt_pk_bf16_f32 v16, v16, s0
	s_mov_b32 s0, 0x125000
	v_add_co_u32_e32 v38, vcc, s0, v106
	v_mfma_f32_16x16x32_bf16 v[12:15], v[94:97], v[82:85], v[70:73]
	s_nop 0
	v_addc_co_u32_e32 v39, vcc, 0, v107, vcc
	global_store_short v[38:39], v16, off offset:512
	v_add_f32_e32 v16, v41, v53
	v_cvt_pk_bf16_f32 v16, v16, s0
	global_store_short v[34:35], v16, off offset:32
	v_add_f32_e32 v16, v37, v53
	v_cvt_pk_bf16_f32 v16, v16, s0
	global_store_short v[34:35], v16, off offset:64
	v_add_f32_e32 v16, v45, v53
	v_cvt_pk_bf16_f32 v16, v16, s0
	global_store_short v[34:35], v16, off offset:96
	v_mov_b32_e32 v34, v208
	v_mov_b32_e32 v35, v209
	v_mov_b32_e32 v36, v210
	v_mov_b32_e32 v37, v211
	s_mov_b64 s[0:1], 0x152a00
	v_lshl_add_u64 v[38:39], v[106:107], 0, s[0:1]
	v_mfma_f32_16x16x32_bf16 v[0:3], v[94:97], v[98:101], v[66:69]
	v_add_f32_e32 v16, v30, v34
	v_cvt_pk_bf16_f32 v16, v16, s0
	s_mov_b32 s0, 0x152000
	v_add_co_u32_e32 v40, vcc, s0, v106
	v_mfma_f32_16x16x32_bf16 v[8:11], v[94:97], v[86:89], v[78:81]
	s_nop 0
	v_addc_co_u32_e32 v41, vcc, 0, v107, vcc
	global_store_short v[40:41], v16, off offset:2560
	v_add_f32_e32 v16, v26, v34
	v_cvt_pk_bf16_f32 v16, v16, s0
	global_store_short v[38:39], v16, off offset:32
	v_add_f32_e32 v16, v18, v34
	v_cvt_pk_bf16_f32 v16, v16, s0
	global_store_short v[38:39], v16, off offset:64
	v_add_f32_e32 v16, v22, v34
	v_cvt_pk_bf16_f32 v16, v16, s0
	global_store_short v[38:39], v16, off offset:96
	s_mov_b64 s[0:1], 0x156200
	v_add_f32_e32 v16, v31, v35
	v_lshl_add_u64 v[38:39], v[106:107], 0, s[0:1]
	v_cvt_pk_bf16_f32 v16, v16, s0
	s_mov_b32 s0, 0x156000
	v_add_co_u32_e32 v30, vcc, s0, v106
	v_mfma_f32_16x16x32_bf16 v[4:7], v[94:97], v[90:93], v[122:125]
	s_nop 0
	v_addc_co_u32_e32 v31, vcc, 0, v107, vcc
	global_store_short v[30:31], v16, off offset:512
	v_add_f32_e32 v16, v27, v35
	v_cvt_pk_bf16_f32 v16, v16, s0
	global_store_short v[38:39], v16, off offset:32
	v_add_f32_e32 v16, v19, v35
	v_cvt_pk_bf16_f32 v16, v16, s0
	global_store_short v[38:39], v16, off offset:64
	v_add_f32_e32 v16, v23, v35
	v_cvt_pk_bf16_f32 v16, v16, s0
	global_store_short v[38:39], v16, off offset:96
	s_mov_b64 s[0:1], 0x159a00
	v_add_f32_e32 v16, v32, v36
	v_lshl_add_u64 v[18:19], v[106:107], 0, s[0:1]
	v_cvt_pk_bf16_f32 v16, v16, s0
	s_mov_b32 s0, 0x159000
	v_add_co_u32_e32 v22, vcc, s0, v106
	s_nop 1
	v_addc_co_u32_e32 v23, vcc, 0, v107, vcc
	global_store_short v[22:23], v16, off offset:2560
	v_add_f32_e32 v16, v28, v36
	v_cvt_pk_bf16_f32 v16, v16, s0
	global_store_short v[18:19], v16, off offset:32
	v_add_f32_e32 v16, v20, v36
	v_cvt_pk_bf16_f32 v16, v16, s0
	global_store_short v[18:19], v16, off offset:64
	v_add_f32_e32 v16, v24, v36
	v_cvt_pk_bf16_f32 v16, v16, s0
	global_store_short v[18:19], v16, off offset:96
	s_mov_b64 s[0:1], 0x15d200
	v_add_f32_e32 v16, v33, v37
	v_lshl_add_u64 v[18:19], v[106:107], 0, s[0:1]
	v_cvt_pk_bf16_f32 v16, v16, s0
	s_mov_b32 s0, 0x15d000
	v_add_co_u32_e32 v22, vcc, s0, v106
	s_nop 1
	v_addc_co_u32_e32 v23, vcc, 0, v107, vcc
	global_store_short v[22:23], v16, off offset:512
	v_add_f32_e32 v16, v29, v37
	v_cvt_pk_bf16_f32 v16, v16, s0
	global_store_short v[18:19], v16, off offset:32
	v_add_f32_e32 v16, v21, v37
	v_cvt_pk_bf16_f32 v16, v16, s0
	global_store_short v[18:19], v16, off offset:64
	v_add_f32_e32 v16, v25, v37
	v_cvt_pk_bf16_f32 v16, v16, s0
	global_store_short v[18:19], v16, off offset:96
	v_mov_b32_e32 v18, v212
	v_mov_b32_e32 v19, v213
	v_mov_b32_e32 v20, v214
	v_mov_b32_e32 v21, v215
	s_mov_b64 s[0:1], 0x18aa00
	v_lshl_add_u64 v[22:23], v[106:107], 0, s[0:1]
	v_add_f32_e32 v12, v12, v18
	v_cvt_pk_bf16_f32 v12, v12, s0
	s_mov_b32 s0, 0x18a000
	v_add_f32_e32 v0, v0, v18
	v_add_f32_e32 v8, v8, v18
	v_add_f32_e32 v4, v4, v18
	v_cvt_pk_bf16_f32 v0, v0, s0
	v_add_co_u32_e32 v24, vcc, s0, v106
	v_cvt_pk_bf16_f32 v8, v8, s0
	v_cvt_pk_bf16_f32 v4, v4, s0
	global_store_short v[22:23], v0, off offset:96
	s_mov_b64 s[0:1], 0x18e200
	v_add_f32_e32 v0, v13, v19
	v_addc_co_u32_e32 v25, vcc, 0, v107, vcc
	global_store_short v[22:23], v8, off offset:32
	global_store_short v[22:23], v4, off offset:64
	v_lshl_add_u64 v[22:23], v[106:107], 0, s[0:1]
	v_cvt_pk_bf16_f32 v0, v0, s0
	s_mov_b32 s0, 0x18e000
	global_store_short v[24:25], v12, off offset:2560
	v_add_co_u32_e32 v12, vcc, s0, v106
	v_add_f32_e32 v4, v14, v20
	s_nop 0
	v_addc_co_u32_e32 v13, vcc, 0, v107, vcc
	global_store_short v[12:13], v0, off offset:512
	v_add_f32_e32 v0, v9, v19
	v_cvt_pk_bf16_f32 v0, v0, s0
	global_store_short v[22:23], v0, off offset:32
	v_add_f32_e32 v0, v5, v19
	v_cvt_pk_bf16_f32 v0, v0, s0
	global_store_short v[22:23], v0, off offset:64
	v_add_f32_e32 v0, v1, v19
	v_cvt_pk_bf16_f32 v0, v0, s0
	s_mov_b64 s[0:1], 0x191a00
	global_store_short v[22:23], v0, off offset:96
	v_lshl_add_u64 v[0:1], v[106:107], 0, s[0:1]
	v_cvt_pk_bf16_f32 v8, v4, s0
	s_mov_b32 s0, 0x191000
	v_add_co_u32_e32 v4, vcc, s0, v106
	v_add_f32_e32 v2, v2, v20
	s_nop 0
	v_addc_co_u32_e32 v5, vcc, 0, v107, vcc
	global_store_short v[4:5], v8, off offset:2560
	v_add_f32_e32 v4, v10, v20
	v_cvt_pk_bf16_f32 v4, v4, s0
	global_store_short v[0:1], v4, off offset:32
	v_add_f32_e32 v4, v6, v20
	v_cvt_pk_bf16_f32 v2, v2, s0
	v_cvt_pk_bf16_f32 v4, v4, s0
	global_store_short v[0:1], v2, off offset:96
	s_mov_b64 s[0:1], 0x195200
	v_add_f32_e32 v2, v15, v21
	global_store_short v[0:1], v4, off offset:64
	v_lshl_add_u64 v[0:1], v[106:107], 0, s[0:1]
	v_cvt_pk_bf16_f32 v2, v2, s0
	s_mov_b32 s0, 0x195000
	v_add_co_u32_e32 v4, vcc, s0, v106
	s_nop 1
	v_addc_co_u32_e32 v5, vcc, 0, v107, vcc
	global_store_short v[4:5], v2, off offset:512
	v_add_f32_e32 v2, v11, v21
	v_cvt_pk_bf16_f32 v2, v2, s0
	global_store_short v[0:1], v2, off offset:32
	v_add_f32_e32 v2, v7, v21
	v_cvt_pk_bf16_f32 v2, v2, s0
	global_store_short v[0:1], v2, off offset:64
	v_add_f32_e32 v2, v3, v21
	v_cvt_pk_bf16_f32 v2, v2, s0
	global_store_short v[0:1], v2, off offset:96
	s_waitcnt lgkmcnt(0)
	s_barrier

.LBB0_744:
	v_lshl_add_u64 v[4:5], s[82:83], 0, v[26:27]
	v_add_co_u32_e32 v6, vcc, 0x2000, v4
	s_nop 4
	v_cvt_pk_bf16_f32 v0, v0, s0
	v_addc_co_u32_e32 v7, vcc, 0, v5, vcc
	global_store_short v[6:7], v0, off offset:1024
	v_add_co_u32_e32 v0, vcc, 0x5000, v4
	v_cvt_pk_bf16_f32 v6, v1, s0
	s_nop 0
	v_addc_co_u32_e32 v1, vcc, 0, v5, vcc
	global_store_short v[0:1], v6, off offset:3072
	v_add_co_u32_e32 v0, vcc, 0x9000, v4
	v_cvt_pk_bf16_f32 v2, v2, s0
	s_nop 0
	v_addc_co_u32_e32 v1, vcc, 0, v5, vcc
	global_store_short v[0:1], v2, off offset:1024
	v_lshl_add_u64 v[0:1], s[34:35], 0, v[24:25]
	v_add_co_u32_e32 v0, vcc, 0xffeef000, v0
	v_cvt_pk_bf16_f32 v2, v3, s0
	s_nop 0
	v_addc_co_u32_e32 v1, vcc, -1, v1, vcc
	global_store_short v[0:1], v2, off offset:-3072
	s_waitcnt lgkmcnt(0)
	s_barrier
	s_add_i32 s20, s20, -1
	s_mov_b64 s[10:11], 0x300
	s_waitcnt vmcnt(0)
	v_perm_b32 v70, v100, v101, s19
	v_perm_b32 v73, v102, v103, s19
	v_perm_b32 v72, v104, v105, s19
	v_perm_b32 v74, v106, v107, s19
	v_perm_b32 v75, v108, v109, s19
	v_perm_b32 v9, v110, v111, s19
	v_perm_b32 v71, v112, v113, s19
	v_perm_b32 v11, v114, v115, s19
	v_perm_b32 v12, v116, v117, s19
	v_perm_b32 v13, v118, v119, s19
	v_perm_b32 v14, v120, v121, s19
	v_perm_b32 v15, v122, v123, s19
	v_perm_b32 v10, v124, v125, s19
	v_perm_b32 v8, v126, v127, s19
	v_perm_b32 v68, v128, v129, s19
	v_perm_b32 v69, v130, v131, s19
	v_mov_b64_e32 v[0:1], v[8:9]
	v_lshl_add_u64 v[18:19], v[18:19], 0, s[10:11]
	v_lshl_add_u64 v[20:21], v[20:21], 0, s[36:37]
	v_lshl_add_u64 v[22:23], v[22:23], 0, s[36:37]
	v_lshl_add_u64 v[24:25], v[24:25], 0, s[36:37]
	v_lshl_add_u64 v[26:27], v[26:27], 0, s[36:37]
	v_lshl_add_u64 v[28:29], v[28:29], 0, s[36:37]
	v_lshl_add_u64 v[30:31], v[30:31], 0, s[36:37]
	v_lshl_add_u64 v[32:33], v[32:33], 0, s[36:37]
	v_lshl_add_u64 v[34:35], v[34:35], 0, s[36:37]
	v_lshl_add_u64 v[36:37], v[36:37], 0, s[36:37]
	s_cmp_eq_u32 s20, 0
	v_mov_b64_e32 v[2:3], v[10:11]
	v_mov_b64_e32 v[4:5], v[12:13]
	v_mov_b64_e32 v[6:7], v[14:15]
	v_mov_b32_e32 v46, v68
	v_mov_b32_e32 v45, v69
	v_mov_b32_e32 v44, v70
	v_mov_b32_e32 v43, v71
	v_mov_b32_e32 v42, v72
	v_mov_b32_e32 v41, v73
	v_mov_b32_e32 v40, v74
	v_mov_b32_e32 v38, v75
	s_cbranch_scc1 .LBB0_755
.LBB0_745:
	v_lshlrev_b32_e32 v39, 16, v55
	v_add_f32_e32 v39, v54, v39
	v_min_f32_e32 v47, 0, v39
	v_mul_f32_e64 v39, |v39|, s87
	v_exp_f32_e32 v39, v39
	s_mov_b32 s10, 0x3d800000
	s_cmp_eq_u32 s20, 1
	v_add_f32_e32 v39, 1.0, v39
	v_cmp_gt_f32_e32 vcc, s27, v39
	s_nop 1
	v_cndmask_b32_e64 v48, 0, 32, vcc
	v_ldexp_f32 v39, v39, v48
	v_log_f32_e32 v39, v39
	s_nop 0
	v_mul_f32_e32 v48, 0x3f317217, v39
	v_fma_f32 v48, v39, s29, -v48
	v_fmac_f32_e32 v48, 0x3377d1cf, v39
	v_fmac_f32_e32 v48, 0x3f317217, v39
	v_cmp_lt_f32_e64 s[64:65], |v39|, s93
	s_nop 1
	v_cndmask_b32_e64 v39, v39, v48, s[64:65]
	v_cndmask_b32_e32 v48, 0, v248, vcc
	v_sub_f32_e32 v39, v39, v48
	v_sub_f32_e32 v39, v47, v39
	v_fma_f32 v76, v39, s10, 0
	v_lshlrev_b32_e32 v39, 16, v56
	v_add_f32_e32 v39, v54, v39
	v_min_f32_e32 v47, 0, v39
	v_mul_f32_e64 v39, |v39|, s87
	v_exp_f32_e32 v39, v39
	s_nop 0
	v_add_f32_e32 v39, 1.0, v39
	v_cmp_gt_f32_e32 vcc, s27, v39
	s_nop 1
	v_cndmask_b32_e64 v48, 0, 32, vcc
	v_ldexp_f32 v39, v39, v48
	v_log_f32_e32 v39, v39
	s_nop 0
	v_mul_f32_e32 v48, 0x3f317217, v39
	v_fma_f32 v48, v39, s29, -v48
	v_fmac_f32_e32 v48, 0x3377d1cf, v39
	v_fmac_f32_e32 v48, 0x3f317217, v39
	v_cmp_lt_f32_e64 s[64:65], |v39|, s93
	s_nop 1
	v_cndmask_b32_e64 v39, v39, v48, s[64:65]
	v_cndmask_b32_e32 v48, 0, v248, vcc
	v_sub_f32_e32 v39, v39, v48
	v_sub_f32_e32 v39, v47, v39
	v_lshlrev_b32_e32 v47, 16, v57
	v_add_f32_e32 v47, v54, v47
	v_min_f32_e32 v48, 0, v47
	v_mul_f32_e64 v47, |v47|, s87
	v_exp_f32_e32 v47, v47
	v_fmamk_f32 v39, v39, 0x3d800000, v76
	v_add_f32_e32 v47, 1.0, v47
	v_cmp_gt_f32_e32 vcc, s27, v47
	s_nop 1
	v_cndmask_b32_e64 v49, 0, 32, vcc
	v_ldexp_f32 v47, v47, v49
	v_log_f32_e32 v47, v47
	s_nop 0
	v_mul_f32_e32 v49, 0x3f317217, v47
	v_fma_f32 v49, v47, s29, -v49
	v_fmac_f32_e32 v49, 0x3377d1cf, v47
	v_fmac_f32_e32 v49, 0x3f317217, v47
	v_cmp_lt_f32_e64 s[64:65], |v47|, s93
	s_nop 1
	v_cndmask_b32_e64 v47, v47, v49, s[64:65]
	v_cndmask_b32_e32 v49, 0, v248, vcc
	v_sub_f32_e32 v47, v47, v49
	v_sub_f32_e32 v47, v48, v47
	v_fmamk_f32 v77, v47, 0x3d800000, v39
	v_lshlrev_b32_e32 v47, 16, v58
	v_add_f32_e32 v47, v54, v47
	v_min_f32_e32 v48, 0, v47
	v_mul_f32_e64 v47, |v47|, s87
	v_exp_f32_e32 v47, v47
	s_nop 0
	v_add_f32_e32 v47, 1.0, v47
	v_cmp_gt_f32_e32 vcc, s27, v47
	s_nop 1
	v_cndmask_b32_e64 v49, 0, 32, vcc
	v_ldexp_f32 v47, v47, v49
	v_log_f32_e32 v47, v47
	s_nop 0
	v_mul_f32_e32 v49, 0x3f317217, v47
	v_fma_f32 v49, v47, s29, -v49
	v_fmac_f32_e32 v49, 0x3377d1cf, v47
	v_fmac_f32_e32 v49, 0x3f317217, v47
	v_cmp_lt_f32_e64 s[64:65], |v47|, s93
	s_nop 1
	v_cndmask_b32_e64 v47, v47, v49, s[64:65]
	v_cndmask_b32_e32 v49, 0, v248, vcc
	v_sub_f32_e32 v47, v47, v49
	v_sub_f32_e32 v47, v48, v47
	v_fmamk_f32 v78, v47, 0x3d800000, v77
	v_lshlrev_b32_e32 v47, 16, v59
	v_add_f32_e32 v47, v54, v47
	v_min_f32_e32 v48, 0, v47
	v_mul_f32_e64 v47, |v47|, s87
	v_exp_f32_e32 v47, v47
	s_nop 0
	v_add_f32_e32 v47, 1.0, v47
	v_cmp_gt_f32_e32 vcc, s27, v47
	s_nop 1
	v_cndmask_b32_e64 v49, 0, 32, vcc
	v_ldexp_f32 v47, v47, v49
	v_log_f32_e32 v47, v47
	s_nop 0
	v_mul_f32_e32 v49, 0x3f317217, v47
	v_fma_f32 v49, v47, s29, -v49
	v_fmac_f32_e32 v49, 0x3377d1cf, v47
	v_fmac_f32_e32 v49, 0x3f317217, v47
	v_cmp_lt_f32_e64 s[64:65], |v47|, s93
	s_nop 1
	v_cndmask_b32_e64 v47, v47, v49, s[64:65]
	v_cndmask_b32_e32 v49, 0, v248, vcc
	v_sub_f32_e32 v47, v47, v49
	v_sub_f32_e32 v47, v48, v47
	v_fmamk_f32 v79, v47, 0x3d800000, v78
	v_lshlrev_b32_e32 v47, 16, v60
	v_add_f32_e32 v47, v54, v47
	v_min_f32_e32 v48, 0, v47
	v_mul_f32_e64 v47, |v47|, s87
	v_exp_f32_e32 v47, v47
	s_nop 0
	v_add_f32_e32 v47, 1.0, v47
	v_cmp_gt_f32_e32 vcc, s27, v47
	s_nop 1
	v_cndmask_b32_e64 v49, 0, 32, vcc
	v_ldexp_f32 v47, v47, v49
	v_log_f32_e32 v47, v47
	s_nop 0
	v_mul_f32_e32 v49, 0x3f317217, v47
	v_fma_f32 v49, v47, s29, -v49
	v_fmac_f32_e32 v49, 0x3377d1cf, v47
	v_fmac_f32_e32 v49, 0x3f317217, v47
	v_cmp_lt_f32_e64 s[64:65], |v47|, s93
	s_nop 1
	v_cndmask_b32_e64 v47, v47, v49, s[64:65]
	v_cndmask_b32_e32 v49, 0, v248, vcc
	v_sub_f32_e32 v47, v47, v49
	v_sub_f32_e32 v47, v48, v47
	v_fmamk_f32 v80, v47, 0x3d800000, v79
	v_lshlrev_b32_e32 v47, 16, v61
	v_add_f32_e32 v47, v54, v47
	v_min_f32_e32 v48, 0, v47
	v_mul_f32_e64 v47, |v47|, s87
	v_exp_f32_e32 v47, v47
	s_nop 0
	v_add_f32_e32 v47, 1.0, v47
	v_cmp_gt_f32_e32 vcc, s27, v47
	s_nop 1
	v_cndmask_b32_e64 v49, 0, 32, vcc
	v_ldexp_f32 v47, v47, v49
	v_log_f32_e32 v47, v47
	s_nop 0
	v_mul_f32_e32 v49, 0x3f317217, v47
	v_fma_f32 v49, v47, s29, -v49
	v_fmac_f32_e32 v49, 0x3377d1cf, v47
	v_fmac_f32_e32 v49, 0x3f317217, v47
	v_cmp_lt_f32_e64 s[64:65], |v47|, s93
	s_nop 1
	v_cndmask_b32_e64 v47, v47, v49, s[64:65]
	v_cndmask_b32_e32 v49, 0, v248, vcc
	v_sub_f32_e32 v47, v47, v49
	v_sub_f32_e32 v47, v48, v47
	v_fmamk_f32 v81, v47, 0x3d800000, v80
	v_lshlrev_b32_e32 v47, 16, v62
	v_add_f32_e32 v47, v54, v47
	v_min_f32_e32 v48, 0, v47
	v_mul_f32_e64 v47, |v47|, s87
	v_exp_f32_e32 v47, v47
	s_nop 0
	v_add_f32_e32 v47, 1.0, v47
	v_cmp_gt_f32_e32 vcc, s27, v47
	s_nop 1
	v_cndmask_b32_e64 v49, 0, 32, vcc
	v_ldexp_f32 v47, v47, v49
	v_log_f32_e32 v47, v47
	s_nop 0
	v_mul_f32_e32 v49, 0x3f317217, v47
	v_fma_f32 v49, v47, s29, -v49
	v_fmac_f32_e32 v49, 0x3377d1cf, v47
	v_fmac_f32_e32 v49, 0x3f317217, v47
	v_cmp_lt_f32_e64 s[64:65], |v47|, s93
	s_nop 1
	v_cndmask_b32_e64 v47, v47, v49, s[64:65]
	v_cndmask_b32_e32 v49, 0, v248, vcc
	v_sub_f32_e32 v47, v47, v49
	v_sub_f32_e32 v47, v48, v47
	v_fmamk_f32 v82, v47, 0x3d800000, v81
	ds_write_b32 v63, v82 offset:34816
	s_waitcnt lgkmcnt(0)
	s_barrier
	s_cbranch_scc1 .LBB0_747
	v_lshl_add_u64 v[8:9], s[82:83], 0, v[20:21]
	v_add_co_u32_e32 v10, vcc, 0xe1000, v8
	s_mov_b32 s10, 0xe2000
	s_nop 0
	v_addc_co_u32_e32 v11, vcc, 0, v9, vcc
	v_add_co_u32_e32 v12, vcc, 0xe2000, v8
	global_load_ushort v131, v[10:11], off offset:3072
	s_nop 0
	v_addc_co_u32_e32 v13, vcc, 0, v9, vcc
	global_load_ushort v55, v[12:13], off offset:1024
	global_load_ushort v129, v[10:11], off offset:3584
	v_add_co_u32_e32 v10, vcc, 0xe5000, v8
	s_nop 1
	v_addc_co_u32_e32 v11, vcc, 0, v9, vcc
	global_load_ushort v130, v[10:11], off offset:1024
	global_load_ushort v56, v[10:11], off offset:3072
	global_load_ushort v128, v[10:11], off offset:1536
	v_add_co_u32_e32 v10, vcc, 0xe8000, v8
	s_nop 1
	v_addc_co_u32_e32 v11, vcc, 0, v9, vcc
	v_add_co_u32_e32 v12, vcc, 0xe9000, v8
	global_load_ushort v113, v[10:11], off offset:3072
	s_nop 0
	v_addc_co_u32_e32 v13, vcc, 0, v9, vcc
	global_load_ushort v57, v[12:13], off offset:1024
	global_load_ushort v101, v[10:11], off offset:3584
	v_add_co_u32_e32 v10, vcc, 0xec000, v8
	s_nop 1
	v_addc_co_u32_e32 v11, vcc, 0, v9, vcc
	global_load_ushort v112, v[10:11], off offset:1024
	global_load_ushort v58, v[10:11], off offset:3072
	global_load_ushort v100, v[10:11], off offset:1536
	v_add_co_u32_e32 v10, vcc, 0xef000, v8
	v_addc_co_u32_e32 v11, vcc, 0, v9, vcc
	v_add_co_u32_e32 v12, vcc, 0xf0000, v8
	global_load_ushort v103, v[10:11], off offset:3072
	s_nop 0
	v_addc_co_u32_e32 v13, vcc, 0, v9, vcc
	global_load_ushort v59, v[12:13], off offset:1024
	global_load_ushort v105, v[10:11], off offset:3584
	v_add_co_u32_e32 v10, vcc, 0xf3000, v8
	s_nop 1
	v_addc_co_u32_e32 v11, vcc, 0, v9, vcc
	global_load_ushort v102, v[10:11], off offset:1024
	global_load_ushort v60, v[10:11], off offset:3072
	global_load_ushort v104, v[10:11], off offset:1536
	v_add_co_u32_e32 v10, vcc, 0xf6000, v8
	v_addc_co_u32_e32 v11, vcc, 0, v9, vcc
	v_add_co_u32_e32 v12, vcc, 0xf7000, v8
	global_load_ushort v109, v[10:11], off offset:3072
	s_nop 0
	v_addc_co_u32_e32 v13, vcc, 0, v9, vcc
	v_add_co_u32_e32 v8, vcc, 0xfa000, v8
	global_load_ushort v61, v[12:13], off offset:1024
	global_load_ushort v107, v[10:11], off offset:3584
	v_addc_co_u32_e32 v9, vcc, 0, v9, vcc
	global_load_ushort v108, v[8:9], off offset:1024
	global_load_ushort v62, v[8:9], off offset:3072
	global_load_ushort v106, v[8:9], off offset:1536
	v_lshl_add_u64 v[8:9], s[82:83], 0, v[22:23]
	v_add_co_u32_e32 v10, vcc, s10, v8
	s_mov_b32 s10, 0xe5000
	s_nop 0
	v_addc_co_u32_e32 v11, vcc, 0, v9, vcc
	global_load_ushort v127, v[10:11], off
	v_add_co_u32_e32 v10, vcc, s10, v8
	s_mov_b32 s10, 0xe9000
	s_nop 0
	v_addc_co_u32_e32 v11, vcc, 0, v9, vcc
	global_load_ushort v126, v[10:11], off offset:2048
	v_add_co_u32_e32 v10, vcc, s10, v8
	s_mov_b32 s10, 0xec000
	s_nop 0
	v_addc_co_u32_e32 v11, vcc, 0, v9, vcc
	global_load_ushort v111, v[10:11], off
	v_add_co_u32_e32 v10, vcc, s10, v8
	s_mov_b32 s10, 0xf0000
	s_nop 0
	v_addc_co_u32_e32 v11, vcc, 0, v9, vcc
	global_load_ushort v110, v[10:11], off offset:2048
	v_add_co_u32_e32 v10, vcc, s10, v8
	s_mov_b32 s10, 0xf3000
	s_nop 0
	v_addc_co_u32_e32 v11, vcc, 0, v9, vcc
	global_load_ushort v125, v[10:11], off
	v_add_co_u32_e32 v10, vcc, s10, v8
	s_mov_b32 s10, 0xf7000
	s_nop 0
	v_addc_co_u32_e32 v11, vcc, 0, v9, vcc
	global_load_ushort v124, v[10:11], off offset:2048
	v_add_co_u32_e32 v10, vcc, s10, v8
	s_mov_b32 s10, 0xfa000
	s_nop 0
	v_addc_co_u32_e32 v11, vcc, 0, v9, vcc
	global_load_ushort v115, v[10:11], off
	v_add_co_u32_e32 v10, vcc, s10, v8
	s_mov_b32 s10, 0xfe000
	s_nop 0
	v_addc_co_u32_e32 v11, vcc, 0, v9, vcc
	global_load_ushort v114, v[10:11], off offset:2048
	v_add_co_u32_e32 v10, vcc, s10, v8
	s_mov_b32 s10, 0x101000
	s_nop 0
	v_addc_co_u32_e32 v11, vcc, 0, v9, vcc
	global_load_ushort v117, v[10:11], off
	v_add_co_u32_e32 v10, vcc, s10, v8
	s_mov_b32 s10, 0x105000
	s_nop 0
	v_addc_co_u32_e32 v11, vcc, 0, v9, vcc
	global_load_ushort v116, v[10:11], off offset:2048
	v_add_co_u32_e32 v10, vcc, s10, v8
	s_mov_b32 s10, 0x108000
	s_nop 0
	v_addc_co_u32_e32 v11, vcc, 0, v9, vcc
	global_load_ushort v119, v[10:11], off
	v_add_co_u32_e32 v10, vcc, s10, v8
	s_mov_b32 s10, 0x10c000
	s_nop 0
	v_addc_co_u32_e32 v11, vcc, 0, v9, vcc
	global_load_ushort v118, v[10:11], off offset:2048
	v_add_co_u32_e32 v10, vcc, s10, v8
	s_mov_b32 s10, 0x10f000
	s_nop 0
	v_addc_co_u32_e32 v11, vcc, 0, v9, vcc
	global_load_ushort v121, v[10:11], off
	v_add_co_u32_e32 v10, vcc, s10, v8
	s_mov_b32 s10, 0x113000
	s_nop 0
	v_addc_co_u32_e32 v11, vcc, 0, v9, vcc
	global_load_ushort v120, v[10:11], off offset:2048
	v_add_co_u32_e32 v10, vcc, s10, v8
	s_mov_b32 s10, 0x116000
	s_nop 0
	v_addc_co_u32_e32 v11, vcc, 0, v9, vcc
	v_add_co_u32_e32 v8, vcc, s10, v8
	global_load_ushort v123, v[10:11], off
	s_nop 0
	v_addc_co_u32_e32 v9, vcc, 0, v9, vcc
	global_load_ushort v122, v[8:9], off offset:2048
